# v86 with default cache policy on the HGRN2 q/k row loads (nt kept on the log-f loads only)
# baseline (speedup 1.0000x reference)
.LBB0_1167:
	s_or_b64 exec, exec, s[0:1]
	s_lshl_b32 s36, s72, 7
	s_ashr_i32 s1, s3, 31
	v_readlane_b32 s0, v251, 10
	s_add_u32 s0, s0, s3
	v_readlane_b32 s3, v251, 11
	s_addc_u32 s1, s3, s1
	s_ashr_i32 s3, s2, 31
	s_lshl_b64 s[6:7], s[36:37], 2
	s_waitcnt lgkmcnt(0)
	s_add_u32 s6, s4, s6
	s_addc_u32 s7, s5, s7
	s_ashr_i32 s5, s8, 31
	s_add_u32 s4, s30, s8
	s_addc_u32 s5, s31, s5
	v_readlane_b32 s8, v254, 15
	s_add_u32 s2, s8, s2
	v_readlane_b32 s8, v254, 16
	v_lshlrev_b32_e32 v74, 1, v18
	s_addc_u32 s3, s8, s3
	v_ashrrev_i32_e32 v75, 31, v74
	v_lshl_add_u64 v[76:77], v[74:75], 2, s[2:3]
	v_readlane_b32 s2, v254, 39
	s_add_u32 s2, s0, s2
	v_readlane_b32 s3, v254, 38
	v_readlane_b32 s8, v254, 14
	s_addc_u32 s3, s1, s3
	s_lshl_b32 s36, s8, 1
	s_add_u32 s2, s2, s36
	s_addc_u32 s3, s3, 0
	v_lshl_add_u64 v[2:3], v[74:75], 1, s[2:3]
	s_mov_b64 s[2:3], 0x2000
	v_lshl_add_u64 v[78:79], v[2:3], 0, s[2:3]
	v_readlane_b32 s2, v254, 42
	v_mov_b64_e32 v[4:5], s[0:1]
	s_movk_i32 s11, 0x4000
	v_add_u32_e32 v6, s2, v18
	v_mad_i64_i32 v[4:5], s[2:3], v6, s28, v[4:5]
	v_add_co_u32_e32 v6, vcc, s66, v2
	s_movk_i32 s3, 0x2000
	s_nop 0
	v_addc_co_u32_e32 v7, vcc, 0, v3, vcc
	v_add_co_u32_e32 v8, vcc, s3, v76
	s_mov_b32 s3, 0x9000
	s_nop 0
	v_addc_co_u32_e32 v9, vcc, 0, v77, vcc
	v_add_co_u32_e32 v10, vcc, s3, v2
	s_mov_b32 s3, 0xf000
	s_nop 0
	v_addc_co_u32_e32 v11, vcc, 0, v3, vcc
	v_add_co_u32_e32 v12, vcc, s11, v76
	v_readlane_b32 s10, v254, 17
	s_nop 0
	v_addc_co_u32_e32 v13, vcc, 0, v77, vcc
	v_add_co_u32_e32 v14, vcc, s3, v2
	s_mov_b32 s3, 0x15000
	s_nop 0
	v_addc_co_u32_e32 v15, vcc, 0, v3, vcc
	v_add_co_u32_e32 v16, vcc, s28, v76
	s_lshl_b32 s8, s10, 1
	s_nop 0
	v_addc_co_u32_e32 v17, vcc, 0, v77, vcc
	v_add_co_u32_e32 v20, vcc, s3, v2
	s_mov_b32 s3, 0x8000
	s_nop 0
	v_addc_co_u32_e32 v21, vcc, 0, v3, vcc
	global_load_dword v75, v[6:7], off offset:-4096
	global_load_dword v125, v[6:7], off
	global_load_dword v126, v[10:11], off offset:-4096
	global_load_dword v127, v[10:11], off
	global_load_dword v128, v[14:15], off offset:-4096
	global_load_dword v129, v[14:15], off
	global_load_dword v130, v[20:21], off offset:-4096
	global_load_dword v131, v[20:21], off
	v_add_co_u32_e32 v6, vcc, s3, v76
	s_mov_b32 s3, 0x1b000
	s_nop 0
	v_addc_co_u32_e32 v7, vcc, 0, v77, vcc
	global_load_dwordx2 v[80:81], v[8:9], off nt
	global_load_dwordx2 v[82:83], v[12:13], off nt
	global_load_dwordx2 v[86:87], v[16:17], off nt
	global_load_dwordx2 v[90:91], v[6:7], off nt
	v_add_co_u32_e32 v6, vcc, s3, v2
	s_mov_b32 s3, 0xa000
	s_nop 0
	v_addc_co_u32_e32 v7, vcc, 0, v3, vcc
	v_add_co_u32_e32 v8, vcc, s3, v76
	s_mov_b32 s3, 0x21000
	s_nop 0
	v_addc_co_u32_e32 v9, vcc, 0, v77, vcc
	v_add_co_u32_e32 v10, vcc, s3, v2
	s_mov_b32 s3, 0xc000
	s_nop 0
	v_addc_co_u32_e32 v11, vcc, 0, v3, vcc
	v_add_co_u32_e32 v12, vcc, s3, v76
	s_mov_b32 s3, 0x27000
	s_nop 0
	v_addc_co_u32_e32 v13, vcc, 0, v77, vcc
	v_add_co_u32_e32 v14, vcc, s3, v2
	s_mov_b32 s3, 0xe000
	s_nop 0
	v_addc_co_u32_e32 v15, vcc, 0, v3, vcc
	v_add_co_u32_e32 v16, vcc, s3, v76
	s_mov_b32 s3, 0x2d000
	s_nop 0
	v_addc_co_u32_e32 v17, vcc, 0, v77, vcc
	v_add_co_u32_e32 v2, vcc, s3, v2
	global_load_dwordx2 v[96:97], v[8:9], off nt
	global_load_dwordx2 v[100:101], v[12:13], off nt
	global_load_dwordx2 v[102:103], v[16:17], off nt
	v_addc_co_u32_e32 v3, vcc, 0, v3, vcc
	global_load_dword v140, v[6:7], off offset:-4096
	global_load_dword v142, v[6:7], off
	global_load_dword v144, v[10:11], off offset:-4096
	global_load_dword v149, v[10:11], off
	global_load_dword v156, v[14:15], off offset:-4096
	global_load_dword v157, v[14:15], off
	global_load_dword v158, v[2:3], off offset:-4096
	global_load_dword v159, v[2:3], off
	v_lshl_add_u64 v[2:3], v[4:5], 0, s[36:37]
	s_mov_b32 s9, s37
	v_ashrrev_i32_e32 v19, 4, v18
	v_lshl_add_u64 v[2:3], v[2:3], 0, s[8:9]
	s_mov_b64 s[8:9], 0x4000
	v_lshl_add_u64 v[84:85], v[2:3], 0, s[8:9]
	v_add_co_u32_e32 v2, vcc, s11, v2
	v_lshlrev_b32_e32 v88, 2, v19
	s_nop 0
	v_addc_co_u32_e32 v3, vcc, 0, v3, vcc
	v_ashrrev_i32_e32 v89, 31, v88
	v_readlane_b32 s8, v254, 47
	global_load_dwordx4 v[22:25], v[2:3], off
	global_load_dwordx2 v[92:93], v[76:77], off nt
	global_load_dwordx4 v[26:29], v[84:85], off offset:16
	v_lshl_add_u64 v[2:3], v[88:89], 2, s[6:7]
	s_lshl_b32 s6, s8, 2
	s_mov_b32 s7, s37
	v_lshl_add_u64 v[14:15], v[2:3], 0, s[6:7]
	global_load_dwordx4 v[2:5], v[14:15], off
	global_load_dwordx4 v[6:9], v[14:15], off offset:64
	global_load_dwordx4 v[10:13], v[14:15], off offset:128
	s_nop 0
	global_load_dwordx4 v[14:17], v[14:15], off offset:192
	v_add_u32_e32 v0, 0, v0
	s_movk_i32 s3, 0x11c
	v_mad_u64_u32 v[20:21], s[6:7], v18, s3, v[0:1]
	v_and_b32_e32 v124, 15, v18
	v_readlane_b32 s7, v254, 25
	v_lshlrev_b32_e32 v132, 3, v18
	v_and_b32_e32 v133, -16, v18
	v_readlane_b32 s3, v254, 43
	s_movk_i32 s11, 0x90
	v_cmp_gt_u32_e64 s[86:87], 16, v18
	v_lshl_add_u32 v135, v18, 2, s7
	v_or_b32_e32 v18, s10, v124
	v_or_b32_e32 v30, s3, v124
	v_mul_lo_u32 v18, v18, s11
	v_mul_lo_u32 v31, v30, s11
	s_add_i32 s3, 0, 0x15c00
	s_add_i32 s6, 0, 0x18000
	v_add_u32_e32 v34, 0, v18
	v_add_u32_e32 v18, s10, v88
	v_sub_u32_e32 v21, v124, v88
	v_add_u32_e32 v31, s3, v31
	s_add_i32 s3, 0, 0x11400
	v_lshlrev_b32_e32 v35, 2, v18
	v_lshl_add_u32 v36, v18, 1, s6
	v_or_b32_e32 v18, s8, v124
	v_add_u32_e32 v32, s3, v133
	v_cmp_gt_i32_e64 s[88:89], 0, v21
	v_cmp_gt_i32_e64 s[90:91], 1, v21
	v_cmp_gt_i32_e64 s[92:93], 2, v21
	v_cmp_gt_i32_e64 s[94:95], 3, v21
	v_mul_u32_u24_e32 v21, 0x90, v18
	v_mul_u32_u24_e32 v37, 0x110, v18
	v_mov_b32_e32 v18, s3
	v_readlane_b32 s3, v254, 44
	v_mul_lo_u32 v30, v30, s29
	v_mad_u32_u24 v137, v124, s11, v18
	v_or_b32_e32 v138, s3, v124
	v_readlane_b32 s3, v255, 9
	v_readlane_b32 s9, v254, 48
	v_add_u32_e32 v30, 0, v30
	v_add_u32_e32 v33, s6, v133
	v_readlane_b32 s7, v254, 24
	v_add_u32_e32 v38, 0x1200, v137
	v_add_u32_e32 v39, 0x2400, v137
	v_add_u32_e32 v40, 0x3600, v137
	v_add_u32_e32 v94, s8, v88
	v_mul_u32_u24_e32 v41, 0x110, v124
	v_lshl_add_u32 v139, v19, 3, s3
	v_readlane_b32 s3, v255, 10
	v_mov_b32_e32 v18, 0
	v_add_u32_e32 v19, 0, v35
	s_mov_b32 s2, 0
	v_add_u32_e32 v134, 0, v133
	v_lshl_add_u32 v136, v124, 2, s7
	v_ashrrev_i32_e32 v95, 31, v94
	v_lshl_add_u64 v[98:99], v[88:89], 0, s[8:9]
	v_add3_u32 v141, v41, v133, s3
	v_add_u32_e32 v143, s10, v20
	v_add_u32_e32 v145, v31, v133
	v_add_u32_e32 v146, v30, v133
	v_add_u32_e32 v147, v32, v21
	v_add_u32_e32 v148, v33, v37
	v_add_u32_e32 v150, v34, v133
	v_add_u32_e32 v151, 0x20800, v19
	v_add_u32_e32 v152, v38, v133
	v_add_u32_e32 v153, v39, v133
	v_add_u32_e32 v154, v40, v133
	v_add_u32_e32 v155, v36, v41
	v_mov_b32_e32 v19, v18
	v_mov_b32_e32 v20, v18
	v_mov_b32_e32 v21, v18
	v_mov_b32_e32 v30, v18
	v_mov_b32_e32 v31, v18
	v_mov_b32_e32 v32, v18
	v_mov_b32_e32 v33, v18
	v_mov_b32_e32 v34, v18
	v_mov_b32_e32 v35, v18
	v_mov_b32_e32 v36, v18
	v_mov_b32_e32 v37, v18
	v_mov_b32_e32 v38, v18
	v_mov_b32_e32 v39, v18
	v_mov_b32_e32 v40, v18
	v_mov_b32_e32 v41, v18
	v_mov_b32_e32 v42, v18
	v_mov_b32_e32 v43, v18
	v_mov_b32_e32 v44, v18
	v_mov_b32_e32 v45, v18
	v_mov_b32_e32 v50, v18
	v_mov_b32_e32 v51, v18
	v_mov_b32_e32 v52, v18
	v_mov_b32_e32 v53, v18
	v_mov_b32_e32 v46, v18
	v_mov_b32_e32 v47, v18
	v_mov_b32_e32 v48, v18
	v_mov_b32_e32 v49, v18
	v_mov_b32_e32 v54, v18
	v_mov_b32_e32 v55, v18
	v_mov_b32_e32 v56, v18
	v_mov_b32_e32 v57, v18
	s_barrier
	s_branch .LBB0_1169

.LBB0_1173:
	v_readlane_b32 s6, v254, 18
	v_readlane_b32 s7, v254, 19
	s_mul_i32 s3, s20, 0x880
	s_nop 0
	v_cndmask_b32_e64 v123, v123, 0, s[6:7]
	v_cndmask_b32_e64 v122, v122, 0, s[6:7]
	v_readlane_b32 s6, v254, 26
	v_pk_add_f32 v[72:73], v[72:73], v[122:123]
	v_readlane_b32 s7, v254, 27
	s_nop 1
	v_cndmask_b32_e64 v73, v123, v73, s[6:7]
	v_cndmask_b32_e64 v72, v122, v72, s[6:7]
	v_readlane_b32 s6, v254, 28
	v_pk_add_f32 v[66:67], v[66:67], v[72:73]
	v_readlane_b32 s7, v254, 29
	s_nop 1
	v_cndmask_b32_e64 v67, v73, v67, s[6:7]
	v_cndmask_b32_e64 v66, v72, v66, s[6:7]
	v_readlane_b32 s6, v254, 30
	v_pk_add_f32 v[68:69], v[68:69], v[66:67]
	v_readlane_b32 s7, v254, 31
	s_nop 1
	v_cndmask_b32_e64 v67, v67, v69, s[6:7]
	v_cndmask_b32_e64 v66, v66, v68, s[6:7]
	v_readlane_b32 s6, v254, 32
	v_pk_add_f32 v[62:63], v[62:63], v[66:67]
	v_readlane_b32 s7, v254, 33
	v_and_b32_e32 v69, 0xffff0000, v125
	v_lshlrev_b32_e32 v68, 16, v125
	v_cndmask_b32_e64 v63, v67, v63, s[6:7]
	v_cndmask_b32_e64 v62, v66, v62, s[6:7]
	v_readlane_b32 s6, v254, 34
	v_pk_add_f32 v[64:65], v[64:65], v[62:63]
	v_readlane_b32 s7, v254, 35
	v_lshlrev_b32_e32 v66, 16, v75
	v_and_b32_e32 v67, 0xffff0000, v75
	s_mov_b32 s10, s8
	s_mul_i32 s10, s10, 0x6000
	s_mov_b32 s11, 0
	v_lshl_add_u64 v[238:239], v[78:79], 0, s[10:11]
	global_load_dword v75, v[238:239], off
	s_add_u32 s10, s10, 0x1000
	v_lshl_add_u64 v[240:241], v[78:79], 0, s[10:11]
	global_load_dword v125, v[240:241], off
	v_cndmask_b32_e64 v63, v63, v65, s[6:7]
	v_cndmask_b32_e64 v62, v62, v64, s[6:7]
	v_readlane_b32 s6, v254, 36
	v_pk_add_f32 v[58:59], v[58:59], v[62:63]
	v_readlane_b32 s7, v254, 37
	s_nop 1
	v_cndmask_b32_e64 v59, v63, v59, s[6:7]
	v_cndmask_b32_e64 v58, v62, v58, s[6:7]
	v_readlane_b32 s6, v254, 40
	v_pk_add_f32 v[60:61], v[60:61], v[58:59]
	v_readlane_b32 s7, v254, 41
	s_nop 1
	v_cndmask_b32_e64 v58, v58, v60, s[6:7]
	v_sub_f32_e32 v60, v120, v70
	v_cndmask_b32_e64 v59, v59, v61, s[6:7]
	v_exp_f32_e32 v64, v60
	v_sub_f32_e32 v60, v121, v71
	v_exp_f32_e32 v65, v60
	v_pk_add_f32 v[60:61], v[118:119], v[58:59]
	s_nop 0
	v_pk_add_f32 v[62:63], v[60:61], v[70:71] neg_lo:[0,1] neg_hi:[0,1]
	v_exp_f32_e32 v60, v60
	v_min_f32_e32 v73, 0x42e60000, v63
	v_min_f32_e64 v63, -v63, s14
	v_min_f32_e32 v72, 0x42e60000, v62
	v_min_f32_e64 v62, -v62, s14
	v_exp_f32_e32 v63, v63
	v_exp_f32_e32 v72, v72
	v_exp_f32_e32 v73, v73
	v_exp_f32_e32 v62, v62
	v_exp_f32_e32 v61, v61
	v_mul_f32_e32 v63, v63, v69
	v_add_u32_e32 v69, s3, v0
	v_mul_f32_e32 v60, v60, v66
	v_mul_f32_e32 v72, v72, v66
	v_mul_f32_e32 v73, v73, v67
	v_mul_f32_e32 v62, v62, v68
	v_cvt_pk_bf16_f32 v68, v72, v73
	ds_write_b32 v69, v68
	v_mul_f32_e32 v61, v61, v67
	v_cvt_pk_bf16_f32 v60, v60, v61
	ds_write_b32 v69, v60 offset:17408
	v_cvt_pk_bf16_f32 v60, v62, v63
	ds_write_b32 v69, v60 offset:34816
	v_pk_add_f32 v[60:61], v[116:117], v[58:59]
	v_mul_f32_e32 v66, v64, v62
	v_mul_f32_e32 v67, v63, v65
	v_pk_add_f32 v[62:63], v[60:61], v[70:71] neg_lo:[0,1] neg_hi:[0,1]
	v_exp_f32_e32 v60, v60
	v_min_f32_e32 v117, 0x42e60000, v62
	v_min_f32_e32 v118, 0x42e60000, v63
	v_min_f32_e64 v62, -v62, s14
	v_exp_f32_e32 v117, v117
	v_exp_f32_e32 v118, v118
	v_exp_f32_e32 v62, v62
	v_min_f32_e64 v63, -v63, s14
	v_exp_f32_e32 v61, v61
	v_exp_f32_e32 v63, v63
	v_lshlrev_b32_e32 v68, 16, v126
	v_and_b32_e32 v72, 0xffff0000, v126
	v_lshlrev_b32_e32 v73, 16, v127
	v_mul_f32_e32 v60, v60, v68
	v_and_b32_e32 v116, 0xffff0000, v127
	s_or_b32 s10, s8, 1
	s_mul_i32 s10, s10, 0x6000
	s_mov_b32 s11, 0
	v_lshl_add_u64 v[238:239], v[78:79], 0, s[10:11]
	global_load_dword v126, v[238:239], off
	s_add_u32 s10, s10, 0x1000
	v_lshl_add_u64 v[240:241], v[78:79], 0, s[10:11]
	global_load_dword v127, v[240:241], off
	v_mul_f32_e32 v117, v117, v68
	v_mul_f32_e32 v118, v118, v72
	v_mul_f32_e32 v62, v62, v73
	v_cvt_pk_bf16_f32 v73, v117, v118
	ds_write_b32 v69, v73 offset:272
	v_mul_f32_e32 v61, v61, v72
	v_cvt_pk_bf16_f32 v60, v60, v61
	v_mul_f32_e32 v63, v63, v116
	ds_write_b32 v69, v60 offset:17680
	v_cvt_pk_bf16_f32 v60, v62, v63
	ds_write_b32 v69, v60 offset:35088
	v_pk_add_f32 v[60:61], v[114:115], v[58:59]
	v_mul_f32_e32 v68, v64, v62
	v_mul_f32_e32 v72, v63, v65
	v_pk_add_f32 v[62:63], v[60:61], v[70:71] neg_lo:[0,1] neg_hi:[0,1]
	v_exp_f32_e32 v60, v60
	v_min_f32_e32 v117, 0x42e60000, v62
	v_min_f32_e32 v118, 0x42e60000, v63
	v_min_f32_e64 v62, -v62, s14
	v_exp_f32_e32 v117, v117
	v_exp_f32_e32 v118, v118
	v_exp_f32_e32 v62, v62
	v_min_f32_e64 v63, -v63, s14
	v_exp_f32_e32 v61, v61
	v_exp_f32_e32 v63, v63
	v_lshlrev_b32_e32 v73, 16, v128
	v_and_b32_e32 v114, 0xffff0000, v128
	v_lshlrev_b32_e32 v115, 16, v129
	v_mul_f32_e32 v60, v60, v73
	v_and_b32_e32 v116, 0xffff0000, v129
	s_or_b32 s10, s8, 2
	s_mul_i32 s10, s10, 0x6000
	s_mov_b32 s11, 0
	v_lshl_add_u64 v[238:239], v[78:79], 0, s[10:11]
	global_load_dword v128, v[238:239], off
	s_add_u32 s10, s10, 0x1000
	v_lshl_add_u64 v[240:241], v[78:79], 0, s[10:11]
	global_load_dword v129, v[240:241], off
	v_mul_f32_e32 v117, v117, v73
	v_mul_f32_e32 v118, v118, v114
	v_mul_f32_e32 v62, v62, v115
	v_cvt_pk_bf16_f32 v115, v117, v118
	ds_write_b32 v69, v115 offset:544
	v_mul_f32_e32 v61, v61, v114
	v_cvt_pk_bf16_f32 v60, v60, v61
	v_mul_f32_e32 v63, v63, v116
	ds_write_b32 v69, v60 offset:17952
	v_cvt_pk_bf16_f32 v60, v62, v63
	ds_write_b32 v69, v60 offset:35360
	v_pk_add_f32 v[60:61], v[112:113], v[58:59]
	v_mul_f32_e32 v73, v64, v62
	v_mul_f32_e32 v114, v63, v65
	v_pk_add_f32 v[62:63], v[60:61], v[70:71] neg_lo:[0,1] neg_hi:[0,1]
	v_exp_f32_e32 v60, v60
	v_min_f32_e32 v117, 0x42e60000, v62
	v_min_f32_e32 v118, 0x42e60000, v63
	v_min_f32_e64 v62, -v62, s14
	v_exp_f32_e32 v117, v117
	v_exp_f32_e32 v118, v118
	v_exp_f32_e32 v62, v62
	v_min_f32_e64 v63, -v63, s14
	v_exp_f32_e32 v61, v61
	v_exp_f32_e32 v63, v63
	v_lshlrev_b32_e32 v112, 16, v130
	v_and_b32_e32 v113, 0xffff0000, v130
	v_lshlrev_b32_e32 v115, 16, v131
	v_mul_f32_e32 v60, v60, v112
	v_and_b32_e32 v116, 0xffff0000, v131
	s_or_b32 s10, s8, 3
	s_mul_i32 s10, s10, 0x6000
	s_mov_b32 s11, 0
	v_lshl_add_u64 v[238:239], v[78:79], 0, s[10:11]
	global_load_dword v130, v[238:239], off
	s_add_u32 s10, s10, 0x1000
	v_lshl_add_u64 v[240:241], v[78:79], 0, s[10:11]
	global_load_dword v131, v[240:241], off
	v_mul_f32_e32 v117, v117, v112
	v_mul_f32_e32 v118, v118, v113
	v_mul_f32_e32 v62, v62, v115
	v_cvt_pk_bf16_f32 v115, v117, v118
	ds_write_b32 v69, v115 offset:816
	v_mul_f32_e32 v61, v61, v113
	v_cvt_pk_bf16_f32 v60, v60, v61
	v_mul_f32_e32 v63, v63, v116
	ds_write_b32 v69, v60 offset:18224
	v_cvt_pk_bf16_f32 v60, v62, v63
	ds_write_b32 v69, v60 offset:35632
	v_pk_add_f32 v[60:61], v[110:111], v[58:59]
	v_mul_f32_e32 v112, v64, v62
	v_mul_f32_e32 v113, v63, v65
	v_pk_add_f32 v[62:63], v[60:61], v[70:71] neg_lo:[0,1] neg_hi:[0,1]
	v_exp_f32_e32 v60, v60
	v_min_f32_e32 v117, 0x42e60000, v62
	v_min_f32_e32 v118, 0x42e60000, v63
	v_min_f32_e64 v62, -v62, s14
	v_exp_f32_e32 v117, v117
	v_exp_f32_e32 v118, v118
	v_exp_f32_e32 v62, v62
	v_min_f32_e64 v63, -v63, s14
	v_exp_f32_e32 v61, v61
	v_exp_f32_e32 v63, v63
	v_lshlrev_b32_e32 v110, 16, v140
	v_and_b32_e32 v111, 0xffff0000, v140
	v_lshlrev_b32_e32 v115, 16, v142
	v_mul_f32_e32 v60, v60, v110
	v_and_b32_e32 v116, 0xffff0000, v142
	s_or_b32 s10, s8, 4
	s_mul_i32 s10, s10, 0x6000
	s_mov_b32 s11, 0
	v_lshl_add_u64 v[238:239], v[78:79], 0, s[10:11]
	global_load_dword v140, v[238:239], off
	s_add_u32 s10, s10, 0x1000
	v_lshl_add_u64 v[240:241], v[78:79], 0, s[10:11]
	global_load_dword v142, v[240:241], off
	v_mul_f32_e32 v117, v117, v110
	v_mul_f32_e32 v118, v118, v111
	v_mul_f32_e32 v62, v62, v115
	v_cvt_pk_bf16_f32 v115, v117, v118
	ds_write_b32 v69, v115 offset:1088
	v_mul_f32_e32 v61, v61, v111
	v_cvt_pk_bf16_f32 v60, v60, v61
	v_mul_f32_e32 v63, v63, v116
	ds_write_b32 v69, v60 offset:18496
	v_cvt_pk_bf16_f32 v60, v62, v63
	ds_write_b32 v69, v60 offset:35904
	v_pk_add_f32 v[60:61], v[108:109], v[58:59]
	v_mul_f32_e32 v110, v64, v62
	v_mul_f32_e32 v111, v63, v65
	v_pk_add_f32 v[62:63], v[60:61], v[70:71] neg_lo:[0,1] neg_hi:[0,1]
	v_exp_f32_e32 v60, v60
	v_min_f32_e32 v117, 0x42e60000, v62
	v_min_f32_e32 v118, 0x42e60000, v63
	v_min_f32_e64 v62, -v62, s14
	v_exp_f32_e32 v117, v117
	v_exp_f32_e32 v118, v118
	v_exp_f32_e32 v62, v62
	v_min_f32_e64 v63, -v63, s14
	v_exp_f32_e32 v61, v61
	v_exp_f32_e32 v63, v63
	v_lshlrev_b32_e32 v108, 16, v144
	v_and_b32_e32 v109, 0xffff0000, v144
	v_lshlrev_b32_e32 v115, 16, v149
	v_mul_f32_e32 v60, v60, v108
	v_and_b32_e32 v116, 0xffff0000, v149
	s_or_b32 s10, s8, 5
	s_mul_i32 s10, s10, 0x6000
	s_mov_b32 s11, 0
	v_lshl_add_u64 v[238:239], v[78:79], 0, s[10:11]
	global_load_dword v144, v[238:239], off
	s_add_u32 s10, s10, 0x1000
	v_lshl_add_u64 v[240:241], v[78:79], 0, s[10:11]
	global_load_dword v149, v[240:241], off
	v_mul_f32_e32 v117, v117, v108
	v_mul_f32_e32 v118, v118, v109
	v_mul_f32_e32 v62, v62, v115
	v_cvt_pk_bf16_f32 v115, v117, v118
	ds_write_b32 v69, v115 offset:1360
	v_mul_f32_e32 v61, v61, v109
	v_cvt_pk_bf16_f32 v60, v60, v61
	v_mul_f32_e32 v63, v63, v116
	ds_write_b32 v69, v60 offset:18768
	v_cvt_pk_bf16_f32 v60, v62, v63
	ds_write_b32 v69, v60 offset:36176
	v_pk_add_f32 v[60:61], v[106:107], v[58:59]
	v_mul_f32_e32 v108, v64, v62
	v_mul_f32_e32 v109, v63, v65
	v_pk_add_f32 v[62:63], v[60:61], v[70:71] neg_lo:[0,1] neg_hi:[0,1]
	v_exp_f32_e32 v60, v60
	v_min_f32_e32 v117, 0x42e60000, v62
	v_min_f32_e32 v118, 0x42e60000, v63
	v_min_f32_e64 v62, -v62, s14
	v_exp_f32_e32 v117, v117
	v_exp_f32_e32 v118, v118
	v_exp_f32_e32 v62, v62
	v_min_f32_e64 v63, -v63, s14
	v_exp_f32_e32 v61, v61
	v_exp_f32_e32 v63, v63
	v_lshlrev_b32_e32 v106, 16, v156
	v_and_b32_e32 v107, 0xffff0000, v156
	v_lshlrev_b32_e32 v115, 16, v157
	v_mul_f32_e32 v60, v60, v106
	v_and_b32_e32 v116, 0xffff0000, v157
	s_or_b32 s10, s8, 6
	s_mul_i32 s10, s10, 0x6000
	s_mov_b32 s11, 0
	v_lshl_add_u64 v[238:239], v[78:79], 0, s[10:11]
	global_load_dword v156, v[238:239], off
	s_add_u32 s10, s10, 0x1000
	v_lshl_add_u64 v[240:241], v[78:79], 0, s[10:11]
	global_load_dword v157, v[240:241], off
	v_mul_f32_e32 v117, v117, v106
	v_mul_f32_e32 v118, v118, v107
	v_mul_f32_e32 v62, v62, v115
	v_cvt_pk_bf16_f32 v115, v117, v118
	ds_write_b32 v69, v115 offset:1632
	v_mul_f32_e32 v61, v61, v107
	v_cvt_pk_bf16_f32 v60, v60, v61
	v_mul_f32_e32 v63, v63, v116
	ds_write_b32 v69, v60 offset:19040
	v_cvt_pk_bf16_f32 v60, v62, v63
	v_pk_add_f32 v[58:59], v[104:105], v[58:59]
	ds_write_b32 v69, v60 offset:36448
	v_pk_add_f32 v[60:61], v[58:59], v[70:71] neg_lo:[0,1] neg_hi:[0,1]
	v_exp_f32_e32 v58, v58
	v_min_f32_e32 v106, 0x42e60000, v60
	v_min_f32_e32 v107, 0x42e60000, v61
	v_min_f32_e64 v60, -v60, s14
	v_exp_f32_e32 v106, v106
	v_exp_f32_e32 v107, v107
	v_exp_f32_e32 v60, v60
	v_min_f32_e64 v61, -v61, s14
	v_exp_f32_e32 v59, v59
	v_exp_f32_e32 v61, v61
	v_lshlrev_b32_e32 v70, 16, v158
	v_and_b32_e32 v71, 0xffff0000, v158
	v_lshlrev_b32_e32 v104, 16, v159
	v_mul_f32_e32 v58, v58, v70
	v_and_b32_e32 v105, 0xffff0000, v159
	s_or_b32 s10, s8, 7
	s_mul_i32 s10, s10, 0x6000
	s_mov_b32 s11, 0
	v_lshl_add_u64 v[238:239], v[78:79], 0, s[10:11]
	global_load_dword v158, v[238:239], off
	s_add_u32 s10, s10, 0x1000
	v_lshl_add_u64 v[240:241], v[78:79], 0, s[10:11]
	global_load_dword v159, v[240:241], off
	v_mul_f32_e32 v106, v106, v70
	v_mul_f32_e32 v107, v107, v71
	v_mul_f32_e32 v60, v60, v104
	v_cvt_pk_bf16_f32 v104, v106, v107
	ds_write_b32 v69, v104 offset:1904
	v_mul_f32_e32 v59, v59, v71
	v_cvt_pk_bf16_f32 v58, v58, v59
	v_mul_f32_e32 v61, v61, v105
	ds_write_b32 v69, v58 offset:19312
	v_cvt_pk_bf16_f32 v58, v60, v61
	ds_write_b32 v69, v58 offset:36720
	v_cvt_pk_bf16_f32 v58, v66, v68
	v_mul_f32_e32 v62, v64, v62
	v_mul_f32_e32 v63, v63, v65
	v_mul_f32_e32 v64, v64, v60
	v_mul_f32_e32 v65, v61, v65
	v_cvt_pk_bf16_f32 v59, v73, v112
	v_cvt_pk_bf16_f32 v60, v110, v108
	v_cvt_pk_bf16_f32 v61, v62, v64
	ds_write_b128 v143, v[58:61] offset:52224
	v_cvt_pk_bf16_f32 v58, v67, v72
	s_add_i32 s3, s2, 1
	v_cvt_pk_bf16_f32 v59, v114, v113
	v_cvt_pk_bf16_f32 v60, v111, v109
	v_cvt_pk_bf16_f32 v61, v63, v65
	ds_write_b128 v143, v[58:61] offset:52368
	v_add_u32_e32 v58, s19, v74
	s_cmp_eq_u32 s2, 31
	ds_write_b16 v58, v22
	ds_write_b16_d16_hi v58, v22 offset:144
	ds_write_b16 v58, v23 offset:288
	ds_write_b16_d16_hi v58, v23 offset:432
	ds_write_b16 v58, v24 offset:576
	ds_write_b16_d16_hi v58, v24 offset:720
	ds_write_b16 v58, v25 offset:864
	ds_write_b16_d16_hi v58, v25 offset:1008
	s_waitcnt vmcnt(28)
	ds_write_b16 v58, v26 offset:1152
	ds_write_b16_d16_hi v58, v26 offset:1296
	ds_write_b16 v58, v27 offset:1440
	ds_write_b16_d16_hi v58, v27 offset:1584
	ds_write_b16 v58, v28 offset:1728
	ds_write_b16_d16_hi v58, v28 offset:1872
	ds_write_b16 v58, v29 offset:2016
	ds_write_b16_d16_hi v58, v29 offset:2160
	s_cbranch_scc1 .LBB0_1175
	s_mul_i32 s6, s3, 0x180000
	s_mov_b32 s7, s37
	v_lshl_add_u64 v[26:27], v[84:85], 0, s[6:7]
	global_load_dwordx4 v[22:25], v[26:27], off
	s_nop 0
	global_load_dwordx4 v[26:29], v[26:27], off offset:16
